# E3 item loop rotated: next item's LDS-DMA issued before the current item's epilogue stores
# speedup vs baseline: 1.0200x; 1.0011x over previous
.LBB0_190:
	v_readlane_b32 s14, v252, 48
	v_readlane_b32 s16, v252, 60
	s_andn2_b64 vcc, exec, s[2:3]
	v_readlane_b32 s15, v252, 49
	v_readlane_b32 s17, v252, 61
	s_cbranch_vccnz .LBB0_193
	v_readlane_b32 s2, v253, 48
	v_readlane_b32 s3, v253, 49
	s_andn2_b64 vcc, exec, s[2:3]
	v_readlane_b32 s2, v254, 49
	v_readlane_b32 s0, v254, 42
	s_mov_b32 s4, s2
	v_readlane_b32 s3, v254, 50
	s_cbranch_vccnz .LBB0_193
	v_mov_b32_e32 v243, 0
	s_ashr_i32 s2, s4, 4
	s_ashr_i32 s3, s2, 31
	s_and_b32 s5, s0, 0xf00
	s_lshl_b64 s[6:7], s[2:3], 8
	s_add_u32 s6, s16, s6
	s_addc_u32 s7, s17, s7
	s_lshl_b64 s[8:9], s[2:3], 14
	v_mov_b32_e32 v240, v204
	s_add_u32 s8, s14, s8
	s_addc_u32 s9, s15, s9
	v_readfirstlane_b32 s10, v240
	s_ashr_i32 s11, s10, 6
	v_bfe_u32 v230, v240, 3, 3
	v_lshl_or_b32 v230, s11, 3, v230
	s_and_b32 s12, s11, 1
	v_add_u32_e32 v232, s5, v230
	v_and_b32_e32 v231, 7, v240
	s_lshl_b32 s13, s12, 2
	v_bfe_u32 v241, v240, 4, 2
	v_ashrrev_i32_e32 v233, 31, v232
	v_bitop3_b32 v231, s13, v231, v241 bitop3:0x36
	v_lshlrev_b64 v[232:233], 15, v[232:233]
	v_lshl_add_u64 v[232:233], s[6:7], 0, v[232:233]
	v_lshlrev_b32_e32 v242, 4, v231
	v_lshl_add_u64 v[232:233], v[232:233], 0, v[242:243]
	s_mov_b64 s[6:7], 0x200000
	v_lshl_add_u64 v[234:235], v[232:233], 0, s[6:7]
	s_mov_b64 s[6:7], 0x400000
	v_lshl_add_u64 v[236:237], v[232:233], 0, s[6:7]
	s_mov_b64 s[6:7], 0x600000
	v_ashrrev_i32_e32 v231, 31, v230
	v_lshl_add_u64 v[238:239], v[232:233], 0, s[6:7]
	v_lshlrev_b64 v[230:231], 8, v[230:231]
	s_lshl_b32 s6, s11, 10
	v_lshl_add_u64 v[230:231], s[8:9], 0, v[230:231]
	s_add_i32 s8, s6, 0
	s_mov_b32 m0, s8
	v_lshl_add_u64 v[230:231], v[230:231], 0, v[242:243]
	global_load_lds_dwordx4 v[232:233], off
	s_add_i32 m0, s8, 0x2000
	s_mov_b64 s[6:7], 0x200080
	global_load_lds_dwordx4 v[234:235], off
	s_add_i32 m0, s8, 0x4000
	v_lshl_add_u64 v[234:235], v[232:233], 0, s[92:93]
	global_load_lds_dwordx4 v[236:237], off
	s_add_i32 m0, s8, 0x6000
	s_nop 0
	global_load_lds_dwordx4 v[238:239], off
	s_add_i32 m0, s8, 0x8000
	s_nop 0
	global_load_lds_dwordx4 v[230:231], off
	s_add_i32 m0, s8, 0xc000
	v_lshl_add_u64 v[230:231], v[230:231], 0, s[92:93]
	global_load_lds_dwordx4 v[234:235], off
	v_lshl_add_u64 v[234:235], v[232:233], 0, s[6:7]
	s_add_i32 m0, s8, 0xe000
	s_mov_b64 s[6:7], 0x400080
	global_load_lds_dwordx4 v[234:235], off
	v_lshl_add_u64 v[234:235], v[232:233], 0, s[6:7]
	s_add_i32 m0, s8, 0x10000
	s_mov_b64 s[6:7], 0x600080
	global_load_lds_dwordx4 v[234:235], off
	v_lshl_add_u64 v[232:233], v[232:233], 0, s[6:7]
	s_add_i32 m0, s8, 0x12000
	s_lshr_b32 s6, s10, 1
	global_load_lds_dwordx4 v[232:233], off
	s_add_i32 m0, s8, 0x14000
	s_and_b32 s6, s6, 0x1ffffc0
	global_load_lds_dwordx4 v[230:231], off
	s_waitcnt vmcnt(0)
.LBB0_192:
	s_waitcnt vmcnt(13)
	v_bfe_u32 v1, v240, 1, 3
	s_waitcnt lgkmcnt(0)
	s_barrier
	v_and_b32_e32 v0, 15, v240
	v_xor_b32_e32 v1, v241, v1
	v_lshlrev_b32_e32 v60, 4, v1
	v_or_b32_e32 v1, s6, v0
	v_lshlrev_b32_e32 v0, 7, v0
	v_lshl_or_b32 v16, s12, 12, v0
	v_or_b32_e32 v61, 0x8000, v16
	v_xor_b32_e32 v62, 64, v60
	v_lshl_add_u32 v24, v1, 7, 0
	v_add_u32_e32 v25, 0, v16
	v_add_u32_e32 v63, v24, v60
	v_add_u32_e32 v20, v25, v60
	v_add_u32_e32 v44, v25, v62
	v_add_u32_e32 v68, v24, v62
	ds_read_b128 v[0:3], v63
	ds_read_b128 v[4:7], v63 offset:2048
	ds_read_b128 v[8:11], v63 offset:4096
	ds_read_b128 v[12:15], v63 offset:6144
	ds_read_b128 v[16:19], v20 offset:32768
	ds_read_b128 v[20:23], v20 offset:34816
	ds_read_b128 v[24:27], v68
	ds_read_b128 v[28:31], v68 offset:2048
	ds_read_b128 v[32:35], v68 offset:4096
	ds_read_b128 v[36:39], v68 offset:6144
	ds_read_b128 v[40:43], v44 offset:32768
	ds_read_b128 v[44:47], v44 offset:34816
	s_waitcnt lgkmcnt(0)
	v_mfma_f32_16x16x32_bf16 v[48:51], v[0:3], v[16:19], 0
	v_mfma_f32_16x16x32_bf16 v[0:3], v[0:3], v[20:23], 0
	v_mfma_f32_16x16x32_bf16 v[52:55], v[4:7], v[16:19], 0
	v_mfma_f32_16x16x32_bf16 v[4:7], v[4:7], v[20:23], 0
	v_mfma_f32_16x16x32_bf16 v[56:59], v[8:11], v[16:19], 0
	v_mfma_f32_16x16x32_bf16 v[8:11], v[8:11], v[20:23], 0
	v_mfma_f32_16x16x32_bf16 v[16:19], v[12:15], v[16:19], 0
	v_mfma_f32_16x16x32_bf16 v[12:15], v[12:15], v[20:23], 0
	v_mfma_f32_16x16x32_bf16 v[20:23], v[24:27], v[40:43], v[48:51]
	v_mfma_f32_16x16x32_bf16 v[0:3], v[24:27], v[44:47], v[0:3]
	v_mfma_f32_16x16x32_bf16 v[24:27], v[28:31], v[40:43], v[52:55]
	v_mfma_f32_16x16x32_bf16 v[4:7], v[28:31], v[44:47], v[4:7]
	v_mfma_f32_16x16x32_bf16 v[28:31], v[32:35], v[40:43], v[56:59]
	v_mfma_f32_16x16x32_bf16 v[8:11], v[32:35], v[44:47], v[8:11]
	v_mfma_f32_16x16x32_bf16 v[16:19], v[36:39], v[40:43], v[16:19]
	v_mfma_f32_16x16x32_bf16 v[12:15], v[36:39], v[44:47], v[12:15]
	s_waitcnt vmcnt(8)
	s_waitcnt lgkmcnt(0)
	s_barrier
	s_add_i32 s6, 0, 0xc000
	v_add3_u32 v52, s6, v60, v61
	v_add3_u32 v76, s6, v62, v61
	ds_read_b128 v[32:35], v63 offset:49152
	ds_read_b128 v[36:39], v63 offset:51200
	ds_read_b128 v[40:43], v63 offset:53248
	ds_read_b128 v[44:47], v63 offset:55296
	ds_read_b128 v[48:51], v52
	ds_read_b128 v[52:55], v52 offset:2048
	ds_read_b128 v[56:59], v68 offset:49152
	ds_read_b128 v[60:63], v68 offset:51200
	ds_read_b128 v[64:67], v68 offset:53248
	ds_read_b128 v[68:71], v68 offset:55296
	ds_read_b128 v[72:75], v76
	ds_read_b128 v[76:79], v76 offset:2048
	s_waitcnt lgkmcnt(0)
	v_mfma_f32_16x16x32_bf16 v[20:23], v[32:35], v[48:51], v[20:23]
	v_mfma_f32_16x16x32_bf16 v[0:3], v[32:35], v[52:55], v[0:3]
	v_mfma_f32_16x16x32_bf16 v[24:27], v[36:39], v[48:51], v[24:27]
	v_mfma_f32_16x16x32_bf16 v[4:7], v[36:39], v[52:55], v[4:7]
	v_mfma_f32_16x16x32_bf16 v[28:31], v[40:43], v[48:51], v[28:31]
	v_mfma_f32_16x16x32_bf16 v[8:11], v[40:43], v[52:55], v[8:11]
	v_mfma_f32_16x16x32_bf16 v[16:19], v[44:47], v[48:51], v[16:19]
	v_mfma_f32_16x16x32_bf16 v[12:15], v[44:47], v[52:55], v[12:15]
	v_mfma_f32_16x16x32_bf16 v[20:23], v[56:59], v[72:75], v[20:23]
	v_mfma_f32_16x16x32_bf16 v[0:3], v[56:59], v[76:79], v[0:3]
	v_mfma_f32_16x16x32_bf16 v[24:27], v[60:63], v[72:75], v[24:27]
	v_mfma_f32_16x16x32_bf16 v[4:7], v[60:63], v[76:79], v[4:7]
	v_mfma_f32_16x16x32_bf16 v[28:31], v[64:67], v[72:75], v[28:31]
	v_mfma_f32_16x16x32_bf16 v[8:11], v[64:67], v[76:79], v[8:11]
	v_mfma_f32_16x16x32_bf16 v[16:19], v[68:71], v[72:75], v[16:19]
	v_mfma_f32_16x16x32_bf16 v[12:15], v[68:71], v[76:79], v[12:15]
	s_nop 0
	v_mov_b32_e32 v32, v204
	s_waitcnt lgkmcnt(0)
	s_barrier
	v_mov_b32_e32 v244, s5
	v_mov_b32_e32 v246, s2
	v_mov_b32_e32 v247, s3
	s_add_i32 s4, s4, s96
	s_add_i32 s0, s0, s74
	s_cmpk_gt_i32 s4, 0x7ff
	s_cbranch_scc1 .Le3_last
	v_mov_b32_e32 v243, 0
	s_ashr_i32 s2, s4, 4
	s_ashr_i32 s3, s2, 31
	s_and_b32 s5, s0, 0xf00
	s_lshl_b64 s[6:7], s[2:3], 8
	s_add_u32 s6, s16, s6
	s_addc_u32 s7, s17, s7
	s_lshl_b64 s[8:9], s[2:3], 14
	v_mov_b32_e32 v240, v204
	s_add_u32 s8, s14, s8
	s_addc_u32 s9, s15, s9
	v_readfirstlane_b32 s10, v240
	s_ashr_i32 s11, s10, 6
	v_bfe_u32 v230, v240, 3, 3
	v_lshl_or_b32 v230, s11, 3, v230
	s_and_b32 s12, s11, 1
	v_add_u32_e32 v232, s5, v230
	v_and_b32_e32 v231, 7, v240
	s_lshl_b32 s13, s12, 2
	v_bfe_u32 v241, v240, 4, 2
	v_ashrrev_i32_e32 v233, 31, v232
	v_bitop3_b32 v231, s13, v231, v241 bitop3:0x36
	v_lshlrev_b64 v[232:233], 15, v[232:233]
	v_lshl_add_u64 v[232:233], s[6:7], 0, v[232:233]
	v_lshlrev_b32_e32 v242, 4, v231
	v_lshl_add_u64 v[232:233], v[232:233], 0, v[242:243]
	s_mov_b64 s[6:7], 0x200000
	v_lshl_add_u64 v[234:235], v[232:233], 0, s[6:7]
	s_mov_b64 s[6:7], 0x400000
	v_lshl_add_u64 v[236:237], v[232:233], 0, s[6:7]
	s_mov_b64 s[6:7], 0x600000
	v_ashrrev_i32_e32 v231, 31, v230
	v_lshl_add_u64 v[238:239], v[232:233], 0, s[6:7]
	v_lshlrev_b64 v[230:231], 8, v[230:231]
	s_lshl_b32 s6, s11, 10
	v_lshl_add_u64 v[230:231], s[8:9], 0, v[230:231]
	s_add_i32 s8, s6, 0
	s_mov_b32 m0, s8
	v_lshl_add_u64 v[230:231], v[230:231], 0, v[242:243]
	global_load_lds_dwordx4 v[232:233], off
	s_add_i32 m0, s8, 0x2000
	s_mov_b64 s[6:7], 0x200080
	global_load_lds_dwordx4 v[234:235], off
	s_add_i32 m0, s8, 0x4000
	v_lshl_add_u64 v[234:235], v[232:233], 0, s[92:93]
	global_load_lds_dwordx4 v[236:237], off
	s_add_i32 m0, s8, 0x6000
	s_nop 0
	global_load_lds_dwordx4 v[238:239], off
	s_add_i32 m0, s8, 0x8000
	s_nop 0
	global_load_lds_dwordx4 v[230:231], off
	s_add_i32 m0, s8, 0xc000
	v_lshl_add_u64 v[230:231], v[230:231], 0, s[92:93]
	global_load_lds_dwordx4 v[234:235], off
	v_lshl_add_u64 v[234:235], v[232:233], 0, s[6:7]
	s_add_i32 m0, s8, 0xe000
	s_mov_b64 s[6:7], 0x400080
	global_load_lds_dwordx4 v[234:235], off
	v_lshl_add_u64 v[234:235], v[232:233], 0, s[6:7]
	s_add_i32 m0, s8, 0x10000
	s_mov_b64 s[6:7], 0x600080
	global_load_lds_dwordx4 v[234:235], off
	v_lshl_add_u64 v[232:233], v[232:233], 0, s[6:7]
	s_add_i32 m0, s8, 0x12000
	s_lshr_b32 s6, s10, 1
	global_load_lds_dwordx4 v[232:233], off
	s_add_i32 m0, s8, 0x14000
	s_and_b32 s6, s6, 0x1ffffc0
	global_load_lds_dwordx4 v[230:231], off
.Le3_last:
	v_cvt_pk_bf16_f32 v20, v20, v21
	v_ashrrev_i32_e32 v33, 1, v32
	v_and_b32_e32 v34, 0xffffffc0, v33
	v_lshrrev_b32_e32 v35, 2, v32
	v_lshrrev_b32_e32 v36, 1, v32
	v_and_b32_e32 v32, 15, v32
	v_add_u32_e32 v34, v244, v34
	v_and_or_b32 v36, v36, 32, v32
	v_and_b32_e32 v35, 12, v35
	v_ashrrev_i32_e32 v32, 10, v34
	v_lshlrev_b32_e32 v188, 7, v36
	v_and_or_b32 v37, v33, s29, v35
	v_ashrrev_i32_e32 v33, 31, v32
	v_cvt_pk_bf16_f32 v21, v22, v23
	v_lshl_add_u64 v[22:23], v[188:189], 0, v[246:247]
	v_or_b32_e32 v188, 0x800, v188
	v_lshlrev_b64 v[32:33], 13, v[32:33]
	v_cvt_pk_bf16_f32 v0, v0, v1
	v_cvt_pk_bf16_f32 v1, v2, v3
	v_lshl_add_u64 v[2:3], v[188:189], 0, v[246:247]
	v_lshl_add_u64 v[2:3], v[2:3], 0, v[32:33]
	v_and_b32_e32 v34, 0x300, v34
	v_lshl_add_u64 v[22:23], v[22:23], 0, v[32:33]
	v_lshlrev_b64 v[2:3], 11, v[2:3]
	v_lshlrev_b64 v[22:23], 11, v[22:23]
	v_lshlrev_b32_e32 v34, 1, v34
	v_mov_b32_e32 v35, v189
	v_lshl_add_u64 v[2:3], s[88:89], 0, v[2:3]
	v_lshl_add_u64 v[22:23], s[88:89], 0, v[22:23]
	v_lshlrev_b32_e32 v36, 1, v37
	v_mov_b32_e32 v37, v189
	v_lshl_add_u64 v[2:3], v[2:3], 0, v[34:35]
	v_lshl_add_u64 v[22:23], v[22:23], 0, v[34:35]
	v_lshl_add_u64 v[2:3], v[2:3], 0, v[36:37]
	v_lshl_add_u64 v[22:23], v[22:23], 0, v[36:37]
	global_store_dwordx2 v[2:3], v[0:1], off
	v_cvt_pk_bf16_f32 v0, v24, v25
	v_cvt_pk_bf16_f32 v1, v26, v27
	global_store_dwordx2 v[22:23], v[0:1], off offset:32
	v_cvt_pk_bf16_f32 v0, v4, v5
	v_cvt_pk_bf16_f32 v1, v6, v7
	global_store_dwordx2 v[2:3], v[0:1], off offset:32
	v_cvt_pk_bf16_f32 v0, v28, v29
	v_cvt_pk_bf16_f32 v1, v30, v31
	global_store_dwordx2 v[22:23], v[0:1], off offset:64
	v_cvt_pk_bf16_f32 v0, v8, v9
	v_cvt_pk_bf16_f32 v1, v10, v11
	global_store_dwordx2 v[2:3], v[0:1], off offset:64
	v_cvt_pk_bf16_f32 v0, v16, v17
	v_cvt_pk_bf16_f32 v1, v18, v19
	global_store_dwordx2 v[22:23], v[0:1], off offset:96
	v_cvt_pk_bf16_f32 v0, v12, v13
	v_cvt_pk_bf16_f32 v1, v14, v15
	global_store_dwordx2 v[22:23], v[20:21], off
	global_store_dwordx2 v[2:3], v[0:1], off offset:96
	s_cmpk_gt_i32 s4, 0x7ff
	s_cbranch_scc0 .LBB0_192
